# v29: split-K tail GEMMs use the natural MFMA orientation so each f32 atomic instruction covers 4 rows x 64 contiguous bytes (was 16 rows x 4 scattered dwords)
# speedup vs baseline: 1.0422x; 1.0086x over previous
; DI u32x2 pack4(f32x4 v) { u32x2 r; r[0] = cvtpk(v[0], v[1]); r[1] = cvtpk(v[2], v[3]); return r; }
; DI float relu_i(float x) { return __int_as_float(max(__float_as_int(x), 0)); }
; template <int EPI>
; DI void gemm_epilogue(const Params& p, f32x4 (&acc)[8][4], int m0, int n0, int wr, int wc, int fr, int fq, u16* Cb, int ldc) {
;     ...
; #pragma clang loop unroll(full)
;       for (int m = 0; m < 8; ++m) {
;         const int row = rbase + m * 16;
;         const f32x4 v = acc[m][n];
;         if (EPI == EPI_QB) {
;           *(u32x2*)(Cb + (size_t)row * ldc + col) = pack4(v * QSC);
;         } else if (EPI == EPI_BF16) {
;           *(u32x2*)(Cb + (size_t)row * ldc + col) = pack4(v);
;         } else if (EPI == EPI_RES) {
;           const f32x4 xv = row < MP ? *(const f32x4*)(p.x_p + (size_t)row * 2048 + col) : *(const f32x4*)(p.x_s + (size_t)(row - MP) * 2048 + col);
;           *(f32x4*)(p.out + O_Y + (size_t)row * 2048 + col) = xv + v;
;           if ((m & 3) == 3) __builtin_amdgcn_sched_barrier(0);
;         } else if (EPI == EPI_RELU2) {
;           f32x4 r = {relu_i(v[0]), relu_i(v[1]), relu_i(v[2]), relu_i(v[3])};
;           *(u32x2*)(p.U + (size_t)row * DFF + col) = pack4(r * r);
;         } else if (EPI == EPI_ACC) {
;           float* d = p.out + O_Y + (size_t)row * 2048 + col;
;           *(f32x4*)d = *(const f32x4*)d + v;
;           if ((m & 3) == 3) __builtin_amdgcn_sched_barrier(0);
;         } else if (EPI == EPI_ATOM) {
; #pragma clang loop unroll(full)
;           for (int j = 0; j < 4; ++j) atomicAdd(p.out + O_Y + (size_t)row * 2048 + col + j, v[j]);
;         }
.Lp6t_04:
	s_waitcnt vmcnt(0)
	s_mov_b64 s[100:101], 0x2000
	v_lshlrev_b32_e32 v232, 6, v160
	v_or3_b32 v232, v232, v168, s13
	v_lshlrev_b32_e32 v160, 2, v232
	v_lshlrev_b32_e32 v233, 2, v166
	v_lshl_or_b32 v233, v167, 7, v233
	v_add_u32_e32 v234, 0x4000, v233
	v_ashrrev_i32_e32 v235, 31, v234
	v_lshlrev_b64 v[234:235], 13, v[234:235]
	v_lshl_add_u64 v[234:235], s[64:65], 0, v[234:235]
	v_lshl_add_u64 v[234:235], v[234:235], 0, v[160:161]
	global_atomic_add_f32 v[234:235], v156, off
	global_atomic_add_f32 v[234:235], v108, off offset:64
	global_atomic_add_f32 v[234:235], v96, off offset:128
	global_atomic_add_f32 v[234:235], v76, off offset:192
	v_lshl_add_u64 v[234:235], v[234:235], 0, s[100:101]
	global_atomic_add_f32 v[234:235], v157, off
	global_atomic_add_f32 v[234:235], v109, off offset:64
	global_atomic_add_f32 v[234:235], v97, off offset:128
	global_atomic_add_f32 v[234:235], v77, off offset:192
	v_lshl_add_u64 v[234:235], v[234:235], 0, s[100:101]
	global_atomic_add_f32 v[234:235], v158, off
	global_atomic_add_f32 v[234:235], v110, off offset:64
	global_atomic_add_f32 v[234:235], v98, off offset:128
	global_atomic_add_f32 v[234:235], v78, off offset:192
	v_lshl_add_u64 v[234:235], v[234:235], 0, s[100:101]
	global_atomic_add_f32 v[234:235], v159, off
	global_atomic_add_f32 v[234:235], v111, off offset:64
	global_atomic_add_f32 v[234:235], v99, off offset:128
	global_atomic_add_f32 v[234:235], v79, off offset:192
	v_add_u32_e32 v236, 0x4010, v233
	v_ashrrev_i32_e32 v237, 31, v236
	v_lshlrev_b64 v[236:237], 13, v[236:237]
	v_lshl_add_u64 v[236:237], s[64:65], 0, v[236:237]
	v_lshl_add_u64 v[236:237], v[236:237], 0, v[160:161]
	global_atomic_add_f32 v[236:237], v140, off
	global_atomic_add_f32 v[236:237], v104, off offset:64
	global_atomic_add_f32 v[236:237], v84, off offset:128
	global_atomic_add_f32 v[236:237], v60, off offset:192
	v_lshl_add_u64 v[236:237], v[236:237], 0, s[100:101]
	global_atomic_add_f32 v[236:237], v141, off
	global_atomic_add_f32 v[236:237], v105, off offset:64
	global_atomic_add_f32 v[236:237], v85, off offset:128
	global_atomic_add_f32 v[236:237], v61, off offset:192
	v_lshl_add_u64 v[236:237], v[236:237], 0, s[100:101]
	global_atomic_add_f32 v[236:237], v142, off
	global_atomic_add_f32 v[236:237], v106, off offset:64
	global_atomic_add_f32 v[236:237], v86, off offset:128
	global_atomic_add_f32 v[236:237], v62, off offset:192
	v_lshl_add_u64 v[236:237], v[236:237], 0, s[100:101]
	global_atomic_add_f32 v[236:237], v143, off
	global_atomic_add_f32 v[236:237], v107, off offset:64
	global_atomic_add_f32 v[236:237], v87, off offset:128
	global_atomic_add_f32 v[236:237], v63, off offset:192
	v_add_u32_e32 v234, 0x4020, v233
	v_ashrrev_i32_e32 v235, 31, v234
	v_lshlrev_b64 v[234:235], 13, v[234:235]
	v_lshl_add_u64 v[234:235], s[64:65], 0, v[234:235]
	v_lshl_add_u64 v[234:235], v[234:235], 0, v[160:161]
	global_atomic_add_f32 v[234:235], v116, off
	global_atomic_add_f32 v[234:235], v92, off offset:64
	global_atomic_add_f32 v[234:235], v72, off offset:128
	global_atomic_add_f32 v[234:235], v44, off offset:192
	v_lshl_add_u64 v[234:235], v[234:235], 0, s[100:101]
	global_atomic_add_f32 v[234:235], v117, off
	global_atomic_add_f32 v[234:235], v93, off offset:64
	global_atomic_add_f32 v[234:235], v73, off offset:128
	global_atomic_add_f32 v[234:235], v45, off offset:192
	v_lshl_add_u64 v[234:235], v[234:235], 0, s[100:101]
	global_atomic_add_f32 v[234:235], v118, off
	global_atomic_add_f32 v[234:235], v94, off offset:64
	global_atomic_add_f32 v[234:235], v74, off offset:128
	global_atomic_add_f32 v[234:235], v46, off offset:192
	v_lshl_add_u64 v[234:235], v[234:235], 0, s[100:101]
	global_atomic_add_f32 v[234:235], v119, off
	global_atomic_add_f32 v[234:235], v95, off offset:64
	global_atomic_add_f32 v[234:235], v75, off offset:128
	global_atomic_add_f32 v[234:235], v47, off offset:192
	v_add_u32_e32 v236, 0x4030, v233
	v_ashrrev_i32_e32 v237, 31, v236
	v_lshlrev_b64 v[236:237], 13, v[236:237]
	v_lshl_add_u64 v[236:237], s[64:65], 0, v[236:237]
	v_lshl_add_u64 v[236:237], v[236:237], 0, v[160:161]
	global_atomic_add_f32 v[236:237], v112, off
	global_atomic_add_f32 v[236:237], v80, off offset:64
	global_atomic_add_f32 v[236:237], v56, off offset:128
	global_atomic_add_f32 v[236:237], v32, off offset:192
	v_lshl_add_u64 v[236:237], v[236:237], 0, s[100:101]
	global_atomic_add_f32 v[236:237], v113, off
	global_atomic_add_f32 v[236:237], v81, off offset:64
	global_atomic_add_f32 v[236:237], v57, off offset:128
	global_atomic_add_f32 v[236:237], v33, off offset:192
	v_lshl_add_u64 v[236:237], v[236:237], 0, s[100:101]
	global_atomic_add_f32 v[236:237], v114, off
	global_atomic_add_f32 v[236:237], v82, off offset:64
	global_atomic_add_f32 v[236:237], v58, off offset:128
	global_atomic_add_f32 v[236:237], v34, off offset:192
	v_lshl_add_u64 v[236:237], v[236:237], 0, s[100:101]
	global_atomic_add_f32 v[236:237], v115, off
	global_atomic_add_f32 v[236:237], v83, off offset:64
; DI u32x2 pack4(f32x4 v) { u32x2 r; r[0] = cvtpk(v[0], v[1]); r[1] = cvtpk(v[2], v[3]); return r; }
; DI float relu_i(float x) { return __int_as_float(max(__float_as_int(x), 0)); }
; template <int EPI>
; DI void gemm_epilogue(const Params& p, f32x4 (&acc)[8][4], int m0, int n0, int wr, int wc, int fr, int fq, u16* Cb, int ldc) {
;     ...
; #pragma clang loop unroll(full)
;       for (int m = 0; m < 8; ++m) {
;         const int row = rbase + m * 16;
;         const f32x4 v = acc[m][n];
;         if (EPI == EPI_QB) {
;           *(u32x2*)(Cb + (size_t)row * ldc + col) = pack4(v * QSC);
;         } else if (EPI == EPI_BF16) {
;           *(u32x2*)(Cb + (size_t)row * ldc + col) = pack4(v);
;         } else if (EPI == EPI_RES) {
;           const f32x4 xv = row < MP ? *(const f32x4*)(p.x_p + (size_t)row * 2048 + col) : *(const f32x4*)(p.x_s + (size_t)(row - MP) * 2048 + col);
;           *(f32x4*)(p.out + O_Y + (size_t)row * 2048 + col) = xv + v;
;           if ((m & 3) == 3) __builtin_amdgcn_sched_barrier(0);
;         } else if (EPI == EPI_RELU2) {
;           f32x4 r = {relu_i(v[0]), relu_i(v[1]), relu_i(v[2]), relu_i(v[3])};
;           *(u32x2*)(p.U + (size_t)row * DFF + col) = pack4(r * r);
;         } else if (EPI == EPI_ACC) {
;           float* d = p.out + O_Y + (size_t)row * 2048 + col;
;           *(f32x4*)d = *(const f32x4*)d + v;
;           if ((m & 3) == 3) __builtin_amdgcn_sched_barrier(0);
;         } else if (EPI == EPI_ATOM) {
; #pragma clang loop unroll(full)
;           for (int j = 0; j < 4; ++j) atomicAdd(p.out + O_Y + (size_t)row * 2048 + col + j, v[j]);
;         }
; __global__ void __launch_bounds__(NTHREADS) fwd_megakernel(Params p) {
;     ...
;   for (int id = bid; id < 128; id += nb) {
	global_atomic_add_f32 v[236:237], v59, off offset:128
	global_atomic_add_f32 v[236:237], v35, off offset:192
	v_add_u32_e32 v234, 0x4040, v233
	v_ashrrev_i32_e32 v235, 31, v234
	v_lshlrev_b64 v[234:235], 13, v[234:235]
	v_lshl_add_u64 v[234:235], s[64:65], 0, v[234:235]
	v_lshl_add_u64 v[234:235], v[234:235], 0, v[160:161]
	global_atomic_add_f32 v[234:235], v100, off
	global_atomic_add_f32 v[234:235], v64, off offset:64
	global_atomic_add_f32 v[234:235], v40, off offset:128
	global_atomic_add_f32 v[234:235], v20, off offset:192
	v_lshl_add_u64 v[234:235], v[234:235], 0, s[100:101]
	global_atomic_add_f32 v[234:235], v101, off
	global_atomic_add_f32 v[234:235], v65, off offset:64
	global_atomic_add_f32 v[234:235], v41, off offset:128
	global_atomic_add_f32 v[234:235], v21, off offset:192
	v_lshl_add_u64 v[234:235], v[234:235], 0, s[100:101]
	global_atomic_add_f32 v[234:235], v102, off
	global_atomic_add_f32 v[234:235], v66, off offset:64
	global_atomic_add_f32 v[234:235], v42, off offset:128
	global_atomic_add_f32 v[234:235], v22, off offset:192
	v_lshl_add_u64 v[234:235], v[234:235], 0, s[100:101]
	global_atomic_add_f32 v[234:235], v103, off
	global_atomic_add_f32 v[234:235], v67, off offset:64
	global_atomic_add_f32 v[234:235], v43, off offset:128
	global_atomic_add_f32 v[234:235], v23, off offset:192
	v_add_u32_e32 v236, 0x4050, v233
	v_ashrrev_i32_e32 v237, 31, v236
	v_lshlrev_b64 v[236:237], 13, v[236:237]
	v_lshl_add_u64 v[236:237], s[64:65], 0, v[236:237]
	v_lshl_add_u64 v[236:237], v[236:237], 0, v[160:161]
	global_atomic_add_f32 v[236:237], v88, off
	global_atomic_add_f32 v[236:237], v52, off offset:64
	global_atomic_add_f32 v[236:237], v28, off offset:128
	global_atomic_add_f32 v[236:237], v12, off offset:192
	v_lshl_add_u64 v[236:237], v[236:237], 0, s[100:101]
	global_atomic_add_f32 v[236:237], v89, off
	global_atomic_add_f32 v[236:237], v53, off offset:64
	global_atomic_add_f32 v[236:237], v29, off offset:128
	global_atomic_add_f32 v[236:237], v13, off offset:192
	v_lshl_add_u64 v[236:237], v[236:237], 0, s[100:101]
	global_atomic_add_f32 v[236:237], v90, off
	global_atomic_add_f32 v[236:237], v54, off offset:64
	global_atomic_add_f32 v[236:237], v30, off offset:128
	global_atomic_add_f32 v[236:237], v14, off offset:192
	v_lshl_add_u64 v[236:237], v[236:237], 0, s[100:101]
	global_atomic_add_f32 v[236:237], v91, off
	global_atomic_add_f32 v[236:237], v55, off offset:64
	global_atomic_add_f32 v[236:237], v31, off offset:128
	global_atomic_add_f32 v[236:237], v15, off offset:192
	v_add_u32_e32 v234, 0x4060, v233
	v_ashrrev_i32_e32 v235, 31, v234
	v_lshlrev_b64 v[234:235], 13, v[234:235]
	v_lshl_add_u64 v[234:235], s[64:65], 0, v[234:235]
	v_lshl_add_u64 v[234:235], v[234:235], 0, v[160:161]
	global_atomic_add_f32 v[234:235], v68, off
	global_atomic_add_f32 v[234:235], v36, off offset:64
	global_atomic_add_f32 v[234:235], v16, off offset:128
	global_atomic_add_f32 v[234:235], v4, off offset:192
	v_lshl_add_u64 v[234:235], v[234:235], 0, s[100:101]
	global_atomic_add_f32 v[234:235], v69, off
	global_atomic_add_f32 v[234:235], v37, off offset:64
	global_atomic_add_f32 v[234:235], v17, off offset:128
	global_atomic_add_f32 v[234:235], v5, off offset:192
	v_lshl_add_u64 v[234:235], v[234:235], 0, s[100:101]
	global_atomic_add_f32 v[234:235], v70, off
	global_atomic_add_f32 v[234:235], v38, off offset:64
	global_atomic_add_f32 v[234:235], v18, off offset:128
	global_atomic_add_f32 v[234:235], v6, off offset:192
	v_lshl_add_u64 v[234:235], v[234:235], 0, s[100:101]
	global_atomic_add_f32 v[234:235], v71, off
	global_atomic_add_f32 v[234:235], v39, off offset:64
	global_atomic_add_f32 v[234:235], v19, off offset:128
	global_atomic_add_f32 v[234:235], v7, off offset:192
	v_add_u32_e32 v236, 0x4070, v233
	v_ashrrev_i32_e32 v237, 31, v236
	v_lshlrev_b64 v[236:237], 13, v[236:237]
	v_lshl_add_u64 v[236:237], s[64:65], 0, v[236:237]
	v_lshl_add_u64 v[236:237], v[236:237], 0, v[160:161]
	global_atomic_add_f32 v[236:237], v48, off
	global_atomic_add_f32 v[236:237], v24, off offset:64
	global_atomic_add_f32 v[236:237], v8, off offset:128
	global_atomic_add_f32 v[236:237], v0, off offset:192
	v_lshl_add_u64 v[236:237], v[236:237], 0, s[100:101]
	global_atomic_add_f32 v[236:237], v49, off
	global_atomic_add_f32 v[236:237], v25, off offset:64
	global_atomic_add_f32 v[236:237], v9, off offset:128
	global_atomic_add_f32 v[236:237], v1, off offset:192
	v_lshl_add_u64 v[236:237], v[236:237], 0, s[100:101]
	global_atomic_add_f32 v[236:237], v50, off
	global_atomic_add_f32 v[236:237], v26, off offset:64
	global_atomic_add_f32 v[236:237], v10, off offset:128
	global_atomic_add_f32 v[236:237], v2, off offset:192
	v_lshl_add_u64 v[236:237], v[236:237], 0, s[100:101]
	global_atomic_add_f32 v[236:237], v51, off
	global_atomic_add_f32 v[236:237], v27, off offset:64
	global_atomic_add_f32 v[236:237], v11, off offset:128
	global_atomic_add_f32 v[236:237], v3, off offset:192
	s_add_i32 s27, s27, s73
	s_cmpk_gt_i32 s27, 0x1f
	s_cbranch_scc1 .LBB0_1925

; template <int EPI>
; DI void gemm_tile(const Params& p, const u16* __restrict__ A, int lda, const u16* __restrict__ Bt, int ldb, int K, int m0, int n0,
;                   char* smem, u16* Cb, int ldc) {
;     ...
; #pragma unroll
;     for (int ks = 0; ks < 2; ++ks) {
;       bf16x8 bfr[4];
; #pragma unroll
;       for (int n = 0; n < 4; ++n) bfr[n] = *(const bf16x8*)(cB + n * 16 * LSTR + (ks ? fo1 : fo0));
; #pragma unroll
;       for (int mh = 0; mh < 2; ++mh) {
;         bf16x8 af[4];
; #pragma unroll
;         for (int m = 0; m < 4; ++m) af[m] = *(const bf16x8*)(cA + (mh * 4 + m) * 16 * LSTR + (ks ? fo1 : fo0));
;         __builtin_amdgcn_s_setprio(1);
; #pragma unroll
;         for (int m = 0; m < 4; ++m)
; #pragma unroll
;           for (int n = 0; n < 4; ++n)
;             acc[mh * 4 + m][n] = EpiSwap<EPI>::v ? __builtin_amdgcn_mfma_f32_16x16x32_bf16(bfr[n], af[m], acc[mh * 4 + m][n], 0, 0, 0)
;                                                  : __builtin_amdgcn_mfma_f32_16x16x32_bf16(af[m], bfr[n], acc[mh * 4 + m][n], 0, 0, 0);
;         __builtin_amdgcn_s_setprio(0);
;       }
.Lp6t_06:
	s_min_i32 s0, s15, 5
	s_lshl_b32 s4, s0, 7
	s_waitcnt vmcnt(0)
	v_lshl_add_u64 v[144:145], v[164:165], 0, s[4:5]
	s_waitcnt vmcnt(5)
	v_add_co_u32_e32 v128, vcc, s8, v144
	s_waitcnt vmcnt(2)
	v_lshl_add_u64 v[152:153], v[162:163], 0, s[4:5]
	v_addc_co_u32_e32 v129, vcc, 0, v145, vcc
	v_add_co_u32_e32 v132, vcc, s8, v152
	global_load_dwordx4 v[120:123], v[144:145], off offset:256
	global_load_dwordx4 v[124:127], v[152:153], off offset:256
	v_addc_co_u32_e32 v133, vcc, 0, v153, vcc
	global_load_dwordx4 v[136:139], v[132:133], off offset:256
	v_add_co_u32_e32 v132, vcc, s10, v144
	global_load_dwordx4 v[128:131], v[128:129], off offset:256
	s_nop 0
	v_addc_co_u32_e32 v133, vcc, 0, v145, vcc
	v_add_co_u32_e32 v146, vcc, s10, v152
	global_load_dwordx4 v[132:135], v[132:133], off offset:256
	s_nop 0
	v_addc_co_u32_e32 v147, vcc, 0, v153, vcc
	v_add_co_u32_e32 v144, vcc, s12, v144
	global_load_dwordx4 v[148:151], v[146:147], off offset:256
	s_nop 0
	v_addc_co_u32_e32 v145, vcc, 0, v145, vcc
	v_add_co_u32_e32 v152, vcc, s12, v152
	s_and_b32 s0, s14, 0x8000
	s_nop 0
	v_addc_co_u32_e32 v153, vcc, 0, v153, vcc
	global_load_dwordx4 v[152:155], v[152:153], off offset:256
	s_lshl_b32 s0, s0, 1
	global_load_dwordx4 v[144:147], v[144:145], off offset:256
	s_add_i32 s0, s0, 0
	v_add3_u32 v175, s0, v169, v171
	v_add3_u32 v192, s0, v170, v171
	v_add_u32_e32 v188, v192, v173
	v_add_u32_e32 v193, v175, v173
	ds_read_b128 v[176:179], v188 offset:32768
	ds_read_b128 v[180:183], v188 offset:34816
	ds_read_b128 v[184:187], v188 offset:36864
	ds_read_b128 v[188:191], v188 offset:38912
	ds_read_b128 v[196:199], v193
	ds_read_b128 v[200:203], v193 offset:2048
	ds_read_b128 v[204:207], v193 offset:4096
	ds_read_b128 v[208:211], v193 offset:6144
	s_add_i32 s15, s15, 1
	s_setprio 1
	s_waitcnt lgkmcnt(3)
	v_mfma_f32_16x16x32_bf16 v[156:159], v[196:199], v[176:179], v[156:159]
	v_mfma_f32_16x16x32_bf16 v[108:111], v[196:199], v[180:183], v[108:111]
	v_mfma_f32_16x16x32_bf16 v[96:99], v[196:199], v[184:187], v[96:99]
	v_mfma_f32_16x16x32_bf16 v[76:79], v[196:199], v[188:191], v[76:79]
	s_waitcnt lgkmcnt(2)
	v_mfma_f32_16x16x32_bf16 v[140:143], v[200:203], v[176:179], v[140:143]
	v_mfma_f32_16x16x32_bf16 v[104:107], v[200:203], v[180:183], v[104:107]
	v_mfma_f32_16x16x32_bf16 v[84:87], v[200:203], v[184:187], v[84:87]
	v_mfma_f32_16x16x32_bf16 v[60:63], v[200:203], v[188:191], v[60:63]
	s_waitcnt lgkmcnt(1)
	v_mfma_f32_16x16x32_bf16 v[116:119], v[204:207], v[176:179], v[116:119]
	v_mfma_f32_16x16x32_bf16 v[92:95], v[204:207], v[180:183], v[92:95]
	v_mfma_f32_16x16x32_bf16 v[72:75], v[204:207], v[184:187], v[72:75]
	v_mfma_f32_16x16x32_bf16 v[44:47], v[204:207], v[188:191], v[44:47]
	s_waitcnt lgkmcnt(0)
	v_mfma_f32_16x16x32_bf16 v[112:115], v[208:211], v[176:179], v[112:115]
	v_mfma_f32_16x16x32_bf16 v[80:83], v[208:211], v[180:183], v[80:83]
	v_mfma_f32_16x16x32_bf16 v[56:59], v[208:211], v[184:187], v[56:59]
	v_mfma_f32_16x16x32_bf16 v[32:35], v[208:211], v[188:191], v[32:35]
	s_setprio 0
	ds_read_b128 v[196:199], v193 offset:8192
	ds_read_b128 v[200:203], v193 offset:10240
	ds_read_b128 v[204:207], v193 offset:12288
	ds_read_b128 v[208:211], v193 offset:14336
	s_setprio 1
	s_waitcnt lgkmcnt(3)
	v_mfma_f32_16x16x32_bf16 v[100:103], v[196:199], v[176:179], v[100:103]
	v_mfma_f32_16x16x32_bf16 v[64:67], v[196:199], v[180:183], v[64:67]
	v_mfma_f32_16x16x32_bf16 v[40:43], v[196:199], v[184:187], v[40:43]
	v_mfma_f32_16x16x32_bf16 v[20:23], v[196:199], v[188:191], v[20:23]
	s_waitcnt lgkmcnt(2)
	v_mfma_f32_16x16x32_bf16 v[88:91], v[200:203], v[176:179], v[88:91]
	v_mfma_f32_16x16x32_bf16 v[52:55], v[200:203], v[180:183], v[52:55]
	v_mfma_f32_16x16x32_bf16 v[28:31], v[200:203], v[184:187], v[28:31]
	v_mfma_f32_16x16x32_bf16 v[12:15], v[200:203], v[188:191], v[12:15]
	s_waitcnt lgkmcnt(1)
; template <int EPI>
; DI void gemm_tile(const Params& p, const u16* __restrict__ A, int lda, const u16* __restrict__ Bt, int ldb, int K, int m0, int n0,
;                   char* smem, u16* Cb, int ldc) {
;     ...
; #pragma unroll
;     for (int ks = 0; ks < 2; ++ks) {
;       bf16x8 bfr[4];
; #pragma unroll
;       for (int n = 0; n < 4; ++n) bfr[n] = *(const bf16x8*)(cB + n * 16 * LSTR + (ks ? fo1 : fo0));
; #pragma unroll
;       for (int mh = 0; mh < 2; ++mh) {
;         bf16x8 af[4];
; #pragma unroll
;         for (int m = 0; m < 4; ++m) af[m] = *(const bf16x8*)(cA + (mh * 4 + m) * 16 * LSTR + (ks ? fo1 : fo0));
;         __builtin_amdgcn_s_setprio(1);
; #pragma unroll
;         for (int m = 0; m < 4; ++m)
; #pragma unroll
;           for (int n = 0; n < 4; ++n)
;             acc[mh * 4 + m][n] = EpiSwap<EPI>::v ? __builtin_amdgcn_mfma_f32_16x16x32_bf16(bfr[n], af[m], acc[mh * 4 + m][n], 0, 0, 0)
;                                                  : __builtin_amdgcn_mfma_f32_16x16x32_bf16(af[m], bfr[n], acc[mh * 4 + m][n], 0, 0, 0);
;         __builtin_amdgcn_s_setprio(0);
;       }
	v_mfma_f32_16x16x32_bf16 v[68:71], v[204:207], v[176:179], v[68:71]
	v_mfma_f32_16x16x32_bf16 v[36:39], v[204:207], v[180:183], v[36:39]
	v_mfma_f32_16x16x32_bf16 v[16:19], v[204:207], v[184:187], v[16:19]
	v_mfma_f32_16x16x32_bf16 v[4:7], v[204:207], v[188:191], v[4:7]
	s_waitcnt lgkmcnt(0)
	v_mfma_f32_16x16x32_bf16 v[48:51], v[208:211], v[176:179], v[48:51]
	v_mfma_f32_16x16x32_bf16 v[24:27], v[208:211], v[180:183], v[24:27]
	v_mfma_f32_16x16x32_bf16 v[8:11], v[208:211], v[184:187], v[8:11]
	v_mfma_f32_16x16x32_bf16 v[0:3], v[208:211], v[188:191], v[0:3]
	s_setprio 0
	v_add_u32_e32 v188, v192, v174
	v_add_u32_e32 v175, v175, v174
	ds_read_b128 v[176:179], v188 offset:32768
	ds_read_b128 v[180:183], v188 offset:34816
	ds_read_b128 v[184:187], v188 offset:36864
	ds_read_b128 v[188:191], v188 offset:38912
	ds_read_b128 v[196:199], v175
	ds_read_b128 v[200:203], v175 offset:2048
	ds_read_b128 v[204:207], v175 offset:4096
	ds_read_b128 v[208:211], v175 offset:6144
	s_setprio 1
	s_waitcnt lgkmcnt(3)
	v_mfma_f32_16x16x32_bf16 v[156:159], v[196:199], v[176:179], v[156:159]
	v_mfma_f32_16x16x32_bf16 v[108:111], v[196:199], v[180:183], v[108:111]
	v_mfma_f32_16x16x32_bf16 v[96:99], v[196:199], v[184:187], v[96:99]
	v_mfma_f32_16x16x32_bf16 v[76:79], v[196:199], v[188:191], v[76:79]
	s_waitcnt lgkmcnt(2)
	v_mfma_f32_16x16x32_bf16 v[140:143], v[200:203], v[176:179], v[140:143]
	v_mfma_f32_16x16x32_bf16 v[104:107], v[200:203], v[180:183], v[104:107]
	v_mfma_f32_16x16x32_bf16 v[84:87], v[200:203], v[184:187], v[84:87]
	v_mfma_f32_16x16x32_bf16 v[60:63], v[200:203], v[188:191], v[60:63]
	s_waitcnt lgkmcnt(1)
	v_mfma_f32_16x16x32_bf16 v[116:119], v[204:207], v[176:179], v[116:119]
	v_mfma_f32_16x16x32_bf16 v[92:95], v[204:207], v[180:183], v[92:95]
	v_mfma_f32_16x16x32_bf16 v[72:75], v[204:207], v[184:187], v[72:75]
	v_mfma_f32_16x16x32_bf16 v[44:47], v[204:207], v[188:191], v[44:47]
	s_waitcnt lgkmcnt(0)
	v_mfma_f32_16x16x32_bf16 v[112:115], v[208:211], v[176:179], v[112:115]
	v_mfma_f32_16x16x32_bf16 v[80:83], v[208:211], v[180:183], v[80:83]
	v_mfma_f32_16x16x32_bf16 v[56:59], v[208:211], v[184:187], v[56:59]
	v_mfma_f32_16x16x32_bf16 v[32:35], v[208:211], v[188:191], v[32:35]
	s_setprio 0
	ds_read_b128 v[196:199], v175 offset:8192
	ds_read_b128 v[200:203], v175 offset:10240
	ds_read_b128 v[204:207], v175 offset:12288
	ds_read_b128 v[208:211], v175 offset:14336
	s_setprio 1
	s_waitcnt lgkmcnt(3)
	v_mfma_f32_16x16x32_bf16 v[100:103], v[196:199], v[176:179], v[100:103]
	v_mfma_f32_16x16x32_bf16 v[64:67], v[196:199], v[180:183], v[64:67]
	v_mfma_f32_16x16x32_bf16 v[40:43], v[196:199], v[184:187], v[40:43]
	v_mfma_f32_16x16x32_bf16 v[20:23], v[196:199], v[188:191], v[20:23]
	s_waitcnt lgkmcnt(2)
	v_mfma_f32_16x16x32_bf16 v[88:91], v[200:203], v[176:179], v[88:91]
	v_mfma_f32_16x16x32_bf16 v[52:55], v[200:203], v[180:183], v[52:55]
	v_mfma_f32_16x16x32_bf16 v[28:31], v[200:203], v[184:187], v[28:31]
	v_mfma_f32_16x16x32_bf16 v[12:15], v[200:203], v[188:191], v[12:15]
	s_waitcnt lgkmcnt(1)
	v_mfma_f32_16x16x32_bf16 v[68:71], v[204:207], v[176:179], v[68:71]
	v_mfma_f32_16x16x32_bf16 v[36:39], v[204:207], v[180:183], v[36:39]
	v_mfma_f32_16x16x32_bf16 v[16:19], v[204:207], v[184:187], v[16:19]
	v_mfma_f32_16x16x32_bf16 v[4:7], v[204:207], v[188:191], v[4:7]
	s_waitcnt lgkmcnt(0)
	v_mfma_f32_16x16x32_bf16 v[48:51], v[208:211], v[176:179], v[48:51]
	v_mfma_f32_16x16x32_bf16 v[24:27], v[208:211], v[180:183], v[24:27]
	v_mfma_f32_16x16x32_bf16 v[8:11], v[208:211], v[184:187], v[8:11]
	v_mfma_f32_16x16x32_bf16 v[0:3], v[208:211], v[188:191], v[0:3]
	s_setprio 0
	s_cmp_lg_u32 s15, 8
	s_mov_b32 s14, s16
	s_cbranch_scc0 .Lp6t_04

; DI u32x2 pack4(f32x4 v) { u32x2 r; r[0] = cvtpk(v[0], v[1]); r[1] = cvtpk(v[2], v[3]); return r; }
; DI float relu_i(float x) { return __int_as_float(max(__float_as_int(x), 0)); }
; template <int EPI>
; DI void gemm_epilogue(const Params& p, f32x4 (&acc)[8][4], int m0, int n0, int wr, int wc, int fr, int fq, u16* Cb, int ldc) {
;     ...
; #pragma clang loop unroll(full)
;       for (int m = 0; m < 8; ++m) {
;         const int row = rbase + m * 16;
;         const f32x4 v = acc[m][n];
;         if (EPI == EPI_QB) {
;           *(u32x2*)(Cb + (size_t)row * ldc + col) = pack4(v * QSC);
;         } else if (EPI == EPI_BF16) {
;           *(u32x2*)(Cb + (size_t)row * ldc + col) = pack4(v);
;         } else if (EPI == EPI_RES) {
;           const f32x4 xv = row < MP ? *(const f32x4*)(p.x_p + (size_t)row * 2048 + col) : *(const f32x4*)(p.x_s + (size_t)(row - MP) * 2048 + col);
;           *(f32x4*)(p.out + O_Y + (size_t)row * 2048 + col) = xv + v;
;           if ((m & 3) == 3) __builtin_amdgcn_sched_barrier(0);
;         } else if (EPI == EPI_RELU2) {
;           f32x4 r = {relu_i(v[0]), relu_i(v[1]), relu_i(v[2]), relu_i(v[3])};
;           *(u32x2*)(p.U + (size_t)row * DFF + col) = pack4(r * r);
;         } else if (EPI == EPI_ACC) {
;           float* d = p.out + O_Y + (size_t)row * 2048 + col;
;           *(f32x4*)d = *(const f32x4*)d + v;
;           if ((m & 3) == 3) __builtin_amdgcn_sched_barrier(0);
;         } else if (EPI == EPI_ATOM) {
; #pragma clang loop unroll(full)
;           for (int j = 0; j < 4; ++j) atomicAdd(p.out + O_Y + (size_t)row * 2048 + col + j, v[j]);
;         }
; __global__ void __launch_bounds__(NTHREADS) fwd_megakernel(Params p) {
;     ...
;   for (int id = bid; id < 256; id += nb) {
;     const int nt = id & 7, kc = id >> 3;
;     gemm_tile<EPI_ATOM>(p, p.U + kc * 256, DFF, p.WT_DOWN + kc * 256, DFF, 256, (MT / 256 - 1) * 256, nt * 256, smem, nullptr, 0);
.LBB0_2004:
	s_waitcnt vmcnt(0)
	s_mov_b64 s[100:101], 0x2000
	v_lshlrev_b32_e32 v232, 6, v160
	v_or3_b32 v232, v232, v168, s13
	v_lshlrev_b32_e32 v160, 2, v232
	v_lshlrev_b32_e32 v233, 2, v166
	v_lshl_or_b32 v233, v167, 7, v233
	v_add_u32_e32 v234, 0x4000, v233
	v_ashrrev_i32_e32 v235, 31, v234
	v_lshlrev_b64 v[234:235], 13, v[234:235]
	v_lshl_add_u64 v[234:235], s[64:65], 0, v[234:235]
	v_lshl_add_u64 v[234:235], v[234:235], 0, v[160:161]
	global_atomic_add_f32 v[234:235], v156, off
	global_atomic_add_f32 v[234:235], v108, off offset:64
	global_atomic_add_f32 v[234:235], v96, off offset:128
	global_atomic_add_f32 v[234:235], v76, off offset:192
	v_lshl_add_u64 v[234:235], v[234:235], 0, s[100:101]
	global_atomic_add_f32 v[234:235], v157, off
	global_atomic_add_f32 v[234:235], v109, off offset:64
	global_atomic_add_f32 v[234:235], v97, off offset:128
	global_atomic_add_f32 v[234:235], v77, off offset:192
	v_lshl_add_u64 v[234:235], v[234:235], 0, s[100:101]
	global_atomic_add_f32 v[234:235], v158, off
	global_atomic_add_f32 v[234:235], v110, off offset:64
	global_atomic_add_f32 v[234:235], v98, off offset:128
	global_atomic_add_f32 v[234:235], v78, off offset:192
	v_lshl_add_u64 v[234:235], v[234:235], 0, s[100:101]
	global_atomic_add_f32 v[234:235], v159, off
	global_atomic_add_f32 v[234:235], v111, off offset:64
	global_atomic_add_f32 v[234:235], v99, off offset:128
	global_atomic_add_f32 v[234:235], v79, off offset:192
	v_add_u32_e32 v236, 0x4010, v233
	v_ashrrev_i32_e32 v237, 31, v236
	v_lshlrev_b64 v[236:237], 13, v[236:237]
	v_lshl_add_u64 v[236:237], s[64:65], 0, v[236:237]
	v_lshl_add_u64 v[236:237], v[236:237], 0, v[160:161]
	global_atomic_add_f32 v[236:237], v140, off
	global_atomic_add_f32 v[236:237], v104, off offset:64
	global_atomic_add_f32 v[236:237], v84, off offset:128
	global_atomic_add_f32 v[236:237], v60, off offset:192
	v_lshl_add_u64 v[236:237], v[236:237], 0, s[100:101]
	global_atomic_add_f32 v[236:237], v141, off
	global_atomic_add_f32 v[236:237], v105, off offset:64
	global_atomic_add_f32 v[236:237], v85, off offset:128
	global_atomic_add_f32 v[236:237], v61, off offset:192
	v_lshl_add_u64 v[236:237], v[236:237], 0, s[100:101]
	global_atomic_add_f32 v[236:237], v142, off
	global_atomic_add_f32 v[236:237], v106, off offset:64
	global_atomic_add_f32 v[236:237], v86, off offset:128
	global_atomic_add_f32 v[236:237], v62, off offset:192
	v_lshl_add_u64 v[236:237], v[236:237], 0, s[100:101]
	global_atomic_add_f32 v[236:237], v143, off
	global_atomic_add_f32 v[236:237], v107, off offset:64
	global_atomic_add_f32 v[236:237], v87, off offset:128
	global_atomic_add_f32 v[236:237], v63, off offset:192
	v_add_u32_e32 v234, 0x4020, v233
	v_ashrrev_i32_e32 v235, 31, v234
	v_lshlrev_b64 v[234:235], 13, v[234:235]
	v_lshl_add_u64 v[234:235], s[64:65], 0, v[234:235]
	v_lshl_add_u64 v[234:235], v[234:235], 0, v[160:161]
	global_atomic_add_f32 v[234:235], v116, off
	global_atomic_add_f32 v[234:235], v92, off offset:64
	global_atomic_add_f32 v[234:235], v72, off offset:128
	global_atomic_add_f32 v[234:235], v44, off offset:192
	v_lshl_add_u64 v[234:235], v[234:235], 0, s[100:101]
	global_atomic_add_f32 v[234:235], v117, off
	global_atomic_add_f32 v[234:235], v93, off offset:64
	global_atomic_add_f32 v[234:235], v73, off offset:128
	global_atomic_add_f32 v[234:235], v45, off offset:192
	v_lshl_add_u64 v[234:235], v[234:235], 0, s[100:101]
	global_atomic_add_f32 v[234:235], v118, off
	global_atomic_add_f32 v[234:235], v94, off offset:64
	global_atomic_add_f32 v[234:235], v74, off offset:128
	global_atomic_add_f32 v[234:235], v46, off offset:192
	v_lshl_add_u64 v[234:235], v[234:235], 0, s[100:101]
	global_atomic_add_f32 v[234:235], v119, off
	global_atomic_add_f32 v[234:235], v95, off offset:64
	global_atomic_add_f32 v[234:235], v75, off offset:128
	global_atomic_add_f32 v[234:235], v47, off offset:192
	v_add_u32_e32 v236, 0x4030, v233
	v_ashrrev_i32_e32 v237, 31, v236
	v_lshlrev_b64 v[236:237], 13, v[236:237]
	v_lshl_add_u64 v[236:237], s[64:65], 0, v[236:237]
	v_lshl_add_u64 v[236:237], v[236:237], 0, v[160:161]
	global_atomic_add_f32 v[236:237], v112, off
	global_atomic_add_f32 v[236:237], v80, off offset:64
	global_atomic_add_f32 v[236:237], v56, off offset:128
	global_atomic_add_f32 v[236:237], v32, off offset:192
	v_lshl_add_u64 v[236:237], v[236:237], 0, s[100:101]
	global_atomic_add_f32 v[236:237], v113, off
	global_atomic_add_f32 v[236:237], v81, off offset:64
	global_atomic_add_f32 v[236:237], v57, off offset:128
	global_atomic_add_f32 v[236:237], v33, off offset:192
	v_lshl_add_u64 v[236:237], v[236:237], 0, s[100:101]
	global_atomic_add_f32 v[236:237], v114, off
	global_atomic_add_f32 v[236:237], v82, off offset:64
	global_atomic_add_f32 v[236:237], v58, off offset:128
	global_atomic_add_f32 v[236:237], v34, off offset:192
	v_lshl_add_u64 v[236:237], v[236:237], 0, s[100:101]
	global_atomic_add_f32 v[236:237], v115, off
	global_atomic_add_f32 v[236:237], v83, off offset:64
; DI u32x2 pack4(f32x4 v) { u32x2 r; r[0] = cvtpk(v[0], v[1]); r[1] = cvtpk(v[2], v[3]); return r; }
; DI float relu_i(float x) { return __int_as_float(max(__float_as_int(x), 0)); }
; template <int EPI>
; DI void gemm_epilogue(const Params& p, f32x4 (&acc)[8][4], int m0, int n0, int wr, int wc, int fr, int fq, u16* Cb, int ldc) {
;     ...
; #pragma clang loop unroll(full)
;       for (int m = 0; m < 8; ++m) {
;         const int row = rbase + m * 16;
;         const f32x4 v = acc[m][n];
;         if (EPI == EPI_QB) {
;           *(u32x2*)(Cb + (size_t)row * ldc + col) = pack4(v * QSC);
;         } else if (EPI == EPI_BF16) {
;           *(u32x2*)(Cb + (size_t)row * ldc + col) = pack4(v);
;         } else if (EPI == EPI_RES) {
;           const f32x4 xv = row < MP ? *(const f32x4*)(p.x_p + (size_t)row * 2048 + col) : *(const f32x4*)(p.x_s + (size_t)(row - MP) * 2048 + col);
;           *(f32x4*)(p.out + O_Y + (size_t)row * 2048 + col) = xv + v;
;           if ((m & 3) == 3) __builtin_amdgcn_sched_barrier(0);
;         } else if (EPI == EPI_RELU2) {
;           f32x4 r = {relu_i(v[0]), relu_i(v[1]), relu_i(v[2]), relu_i(v[3])};
;           *(u32x2*)(p.U + (size_t)row * DFF + col) = pack4(r * r);
;         } else if (EPI == EPI_ACC) {
;           float* d = p.out + O_Y + (size_t)row * 2048 + col;
;           *(f32x4*)d = *(const f32x4*)d + v;
;           if ((m & 3) == 3) __builtin_amdgcn_sched_barrier(0);
;         } else if (EPI == EPI_ATOM) {
; #pragma clang loop unroll(full)
;           for (int j = 0; j < 4; ++j) atomicAdd(p.out + O_Y + (size_t)row * 2048 + col + j, v[j]);
;         }
; __global__ void __launch_bounds__(NTHREADS) fwd_megakernel(Params p) {
;     ...
;   for (int id = bid; id < 256; id += nb) {
	global_atomic_add_f32 v[236:237], v59, off offset:128
	global_atomic_add_f32 v[236:237], v35, off offset:192
	v_add_u32_e32 v234, 0x4040, v233
	v_ashrrev_i32_e32 v235, 31, v234
	v_lshlrev_b64 v[234:235], 13, v[234:235]
	v_lshl_add_u64 v[234:235], s[64:65], 0, v[234:235]
	v_lshl_add_u64 v[234:235], v[234:235], 0, v[160:161]
	global_atomic_add_f32 v[234:235], v100, off
	global_atomic_add_f32 v[234:235], v64, off offset:64
	global_atomic_add_f32 v[234:235], v40, off offset:128
	global_atomic_add_f32 v[234:235], v20, off offset:192
	v_lshl_add_u64 v[234:235], v[234:235], 0, s[100:101]
	global_atomic_add_f32 v[234:235], v101, off
	global_atomic_add_f32 v[234:235], v65, off offset:64
	global_atomic_add_f32 v[234:235], v41, off offset:128
	global_atomic_add_f32 v[234:235], v21, off offset:192
	v_lshl_add_u64 v[234:235], v[234:235], 0, s[100:101]
	global_atomic_add_f32 v[234:235], v102, off
	global_atomic_add_f32 v[234:235], v66, off offset:64
	global_atomic_add_f32 v[234:235], v42, off offset:128
	global_atomic_add_f32 v[234:235], v22, off offset:192
	v_lshl_add_u64 v[234:235], v[234:235], 0, s[100:101]
	global_atomic_add_f32 v[234:235], v103, off
	global_atomic_add_f32 v[234:235], v67, off offset:64
	global_atomic_add_f32 v[234:235], v43, off offset:128
	global_atomic_add_f32 v[234:235], v23, off offset:192
	v_add_u32_e32 v236, 0x4050, v233
	v_ashrrev_i32_e32 v237, 31, v236
	v_lshlrev_b64 v[236:237], 13, v[236:237]
	v_lshl_add_u64 v[236:237], s[64:65], 0, v[236:237]
	v_lshl_add_u64 v[236:237], v[236:237], 0, v[160:161]
	global_atomic_add_f32 v[236:237], v88, off
	global_atomic_add_f32 v[236:237], v52, off offset:64
	global_atomic_add_f32 v[236:237], v28, off offset:128
	global_atomic_add_f32 v[236:237], v12, off offset:192
	v_lshl_add_u64 v[236:237], v[236:237], 0, s[100:101]
	global_atomic_add_f32 v[236:237], v89, off
	global_atomic_add_f32 v[236:237], v53, off offset:64
	global_atomic_add_f32 v[236:237], v29, off offset:128
	global_atomic_add_f32 v[236:237], v13, off offset:192
	v_lshl_add_u64 v[236:237], v[236:237], 0, s[100:101]
	global_atomic_add_f32 v[236:237], v90, off
	global_atomic_add_f32 v[236:237], v54, off offset:64
	global_atomic_add_f32 v[236:237], v30, off offset:128
	global_atomic_add_f32 v[236:237], v14, off offset:192
	v_lshl_add_u64 v[236:237], v[236:237], 0, s[100:101]
	global_atomic_add_f32 v[236:237], v91, off
	global_atomic_add_f32 v[236:237], v55, off offset:64
	global_atomic_add_f32 v[236:237], v31, off offset:128
	global_atomic_add_f32 v[236:237], v15, off offset:192
	v_add_u32_e32 v234, 0x4060, v233
	v_ashrrev_i32_e32 v235, 31, v234
	v_lshlrev_b64 v[234:235], 13, v[234:235]
	v_lshl_add_u64 v[234:235], s[64:65], 0, v[234:235]
	v_lshl_add_u64 v[234:235], v[234:235], 0, v[160:161]
	global_atomic_add_f32 v[234:235], v68, off
	global_atomic_add_f32 v[234:235], v36, off offset:64
	global_atomic_add_f32 v[234:235], v16, off offset:128
	global_atomic_add_f32 v[234:235], v4, off offset:192
	v_lshl_add_u64 v[234:235], v[234:235], 0, s[100:101]
	global_atomic_add_f32 v[234:235], v69, off
	global_atomic_add_f32 v[234:235], v37, off offset:64
	global_atomic_add_f32 v[234:235], v17, off offset:128
	global_atomic_add_f32 v[234:235], v5, off offset:192
	v_lshl_add_u64 v[234:235], v[234:235], 0, s[100:101]
	global_atomic_add_f32 v[234:235], v70, off
	global_atomic_add_f32 v[234:235], v38, off offset:64
	global_atomic_add_f32 v[234:235], v18, off offset:128
	global_atomic_add_f32 v[234:235], v6, off offset:192
	v_lshl_add_u64 v[234:235], v[234:235], 0, s[100:101]
	global_atomic_add_f32 v[234:235], v71, off
	global_atomic_add_f32 v[234:235], v39, off offset:64
	global_atomic_add_f32 v[234:235], v19, off offset:128
	global_atomic_add_f32 v[234:235], v7, off offset:192
	v_add_u32_e32 v236, 0x4070, v233
	v_ashrrev_i32_e32 v237, 31, v236
	v_lshlrev_b64 v[236:237], 13, v[236:237]
	v_lshl_add_u64 v[236:237], s[64:65], 0, v[236:237]
	v_lshl_add_u64 v[236:237], v[236:237], 0, v[160:161]
	global_atomic_add_f32 v[236:237], v48, off
	global_atomic_add_f32 v[236:237], v24, off offset:64
	global_atomic_add_f32 v[236:237], v8, off offset:128
	global_atomic_add_f32 v[236:237], v0, off offset:192
	v_lshl_add_u64 v[236:237], v[236:237], 0, s[100:101]
	global_atomic_add_f32 v[236:237], v49, off
	global_atomic_add_f32 v[236:237], v25, off offset:64
	global_atomic_add_f32 v[236:237], v9, off offset:128
	global_atomic_add_f32 v[236:237], v1, off offset:192
	v_lshl_add_u64 v[236:237], v[236:237], 0, s[100:101]
	global_atomic_add_f32 v[236:237], v50, off
	global_atomic_add_f32 v[236:237], v26, off offset:64
	global_atomic_add_f32 v[236:237], v10, off offset:128
	global_atomic_add_f32 v[236:237], v2, off offset:192
	v_lshl_add_u64 v[236:237], v[236:237], 0, s[100:101]
	global_atomic_add_f32 v[236:237], v51, off
	global_atomic_add_f32 v[236:237], v27, off offset:64
	global_atomic_add_f32 v[236:237], v11, off offset:128
	global_atomic_add_f32 v[236:237], v3, off offset:192
	s_add_i32 s72, s72, s73
	s_cmpk_gt_i32 s72, 0x3f
	s_cbranch_scc1 .LBB0_2011

; #define G_LOAD(T) { const int k_ = (T) << 6; _Pragma("unroll") for (int i = 0; i < 4; ++i) { \
;     ra[i] = *(const u32x4*)(Ag + (size_t)(i * 64) * lda + k_); rb[i] = *(const u32x4*)(Bg + (size_t)(i * 64) * ldb + k_); } }
; #define L_STORE(ST) { u16* dA_ = sbase + (ST) * GSTAGE + lr * LSTR + lkw; u16* dB_ = dA_ + 256 * LSTR; _Pragma("unroll") for (int i = 0; i < 4; ++i) { \
;     *(u32x4*)(dA_ + i * 64 * LSTR) = ra[i]; *(u32x4*)(dB_ + i * 64 * LSTR) = rb[i]; } }
; template <int EPI>
; DI void gemm_tile(const Params& p, const u16* __restrict__ A, int lda, const u16* __restrict__ Bt, int ldb, int K, int m0, int n0,
;                   char* smem, u16* Cb, int ldc) {
;     ...
;   for (int kt = 0; kt < nk; ++kt) {
;     __syncthreads();
;     if (kt + 1 < nk) L_STORE((kt + 1) & 1)
;     G_LOAD(min(kt + 2, nk - 1))
;     const u16* cA = sbase + (kt & 1) * GSTAGE + (wr * 128 + fr) * LSTR;
;     const u16* cB = sbase + (kt & 1) * GSTAGE + 256 * LSTR + (wc * 64 + fr) * LSTR;
; #pragma unroll
;     for (int ks = 0; ks < 2; ++ks) {
;       bf16x8 bfr[4];
; #pragma unroll
;       for (int n = 0; n < 4; ++n) bfr[n] = *(const bf16x8*)(cB + n * 16 * LSTR + (ks ? fo1 : fo0));
; #pragma unroll
;       for (int mh = 0; mh < 2; ++mh) {
;         bf16x8 af[4];
; #pragma unroll
;         for (int m = 0; m < 4; ++m) af[m] = *(const bf16x8*)(cA + (mh * 4 + m) * 16 * LSTR + (ks ? fo1 : fo0));
;         __builtin_amdgcn_s_setprio(1);
; #pragma unroll
;         for (int m = 0; m < 4; ++m)
; #pragma unroll
;           for (int n = 0; n < 4; ++n)
;             acc[mh * 4 + m][n] = EpiSwap<EPI>::v ? __builtin_amdgcn_mfma_f32_16x16x32_bf16(bfr[n], af[m], acc[mh * 4 + m][n], 0, 0, 0)
;                                                  : __builtin_amdgcn_mfma_f32_16x16x32_bf16(af[m], bfr[n], acc[mh * 4 + m][n], 0, 0, 0);
;         __builtin_amdgcn_s_setprio(0);
;       }
.LBB0_2006:
	s_and_b32 s0, s14, 0x8000
	s_lshl_b32 s0, s0, 1
	s_add_i32 s0, s0, 0
	v_add3_u32 v175, s0, v169, v171
	v_add3_u32 v192, s0, v170, v171
	v_add_u32_e32 v188, v192, v173
	v_add_u32_e32 v193, v175, v173
	ds_read_b128 v[176:179], v188 offset:32768
	ds_read_b128 v[180:183], v188 offset:34816
	ds_read_b128 v[184:187], v188 offset:36864
	ds_read_b128 v[188:191], v188 offset:38912
	ds_read_b128 v[196:199], v193
	ds_read_b128 v[200:203], v193 offset:2048
	ds_read_b128 v[204:207], v193 offset:4096
	ds_read_b128 v[208:211], v193 offset:6144
	s_min_i32 s0, s15, 13
	s_lshl_b32 s4, s0, 7
	s_waitcnt vmcnt(0)
	v_lshl_add_u64 v[144:145], v[164:165], 0, s[4:5]
	s_waitcnt vmcnt(5)
	v_add_co_u32_e32 v128, vcc, s8, v144
	s_waitcnt vmcnt(2)
	v_lshl_add_u64 v[152:153], v[162:163], 0, s[4:5]
	v_addc_co_u32_e32 v129, vcc, 0, v145, vcc
	v_add_co_u32_e32 v132, vcc, s8, v152
	global_load_dwordx4 v[120:123], v[144:145], off offset:256
	global_load_dwordx4 v[124:127], v[152:153], off offset:256
	v_addc_co_u32_e32 v133, vcc, 0, v153, vcc
	global_load_dwordx4 v[136:139], v[132:133], off offset:256
	v_add_co_u32_e32 v132, vcc, s10, v144
	global_load_dwordx4 v[128:131], v[128:129], off offset:256
	s_nop 0
	v_addc_co_u32_e32 v133, vcc, 0, v145, vcc
	v_add_co_u32_e32 v146, vcc, s10, v152
	global_load_dwordx4 v[132:135], v[132:133], off offset:256
	s_nop 0
	v_addc_co_u32_e32 v147, vcc, 0, v153, vcc
	v_add_co_u32_e32 v144, vcc, s12, v144
	global_load_dwordx4 v[148:151], v[146:147], off offset:256
	s_nop 0
	v_addc_co_u32_e32 v145, vcc, 0, v145, vcc
	v_add_co_u32_e32 v152, vcc, s12, v152
	s_nop 0
	s_nop 0
	v_addc_co_u32_e32 v153, vcc, 0, v153, vcc
	global_load_dwordx4 v[152:155], v[152:153], off offset:256
	s_nop 0
	global_load_dwordx4 v[144:147], v[144:145], off offset:256
	s_add_i32 s15, s15, 1
	s_setprio 1
	s_waitcnt lgkmcnt(3)
	v_mfma_f32_16x16x32_bf16 v[156:159], v[196:199], v[176:179], v[156:159]
	v_mfma_f32_16x16x32_bf16 v[108:111], v[196:199], v[180:183], v[108:111]
	v_mfma_f32_16x16x32_bf16 v[96:99], v[196:199], v[184:187], v[96:99]
	v_mfma_f32_16x16x32_bf16 v[76:79], v[196:199], v[188:191], v[76:79]
	s_waitcnt lgkmcnt(2)
	v_mfma_f32_16x16x32_bf16 v[140:143], v[200:203], v[176:179], v[140:143]
	v_mfma_f32_16x16x32_bf16 v[104:107], v[200:203], v[180:183], v[104:107]
	v_mfma_f32_16x16x32_bf16 v[84:87], v[200:203], v[184:187], v[84:87]
	v_mfma_f32_16x16x32_bf16 v[60:63], v[200:203], v[188:191], v[60:63]
	s_waitcnt lgkmcnt(1)
	v_mfma_f32_16x16x32_bf16 v[116:119], v[204:207], v[176:179], v[116:119]
	v_mfma_f32_16x16x32_bf16 v[92:95], v[204:207], v[180:183], v[92:95]
	v_mfma_f32_16x16x32_bf16 v[72:75], v[204:207], v[184:187], v[72:75]
	v_mfma_f32_16x16x32_bf16 v[44:47], v[204:207], v[188:191], v[44:47]
	s_waitcnt lgkmcnt(0)
	v_mfma_f32_16x16x32_bf16 v[112:115], v[208:211], v[176:179], v[112:115]
	v_mfma_f32_16x16x32_bf16 v[80:83], v[208:211], v[180:183], v[80:83]
	v_mfma_f32_16x16x32_bf16 v[56:59], v[208:211], v[184:187], v[56:59]
	v_mfma_f32_16x16x32_bf16 v[32:35], v[208:211], v[188:191], v[32:35]
	s_setprio 0
	ds_read_b128 v[196:199], v193 offset:8192
	ds_read_b128 v[200:203], v193 offset:10240
	ds_read_b128 v[204:207], v193 offset:12288
	ds_read_b128 v[208:211], v193 offset:14336
	s_setprio 1
	s_waitcnt lgkmcnt(3)
	v_mfma_f32_16x16x32_bf16 v[100:103], v[196:199], v[176:179], v[100:103]
	v_mfma_f32_16x16x32_bf16 v[64:67], v[196:199], v[180:183], v[64:67]
	v_mfma_f32_16x16x32_bf16 v[40:43], v[196:199], v[184:187], v[40:43]
	v_mfma_f32_16x16x32_bf16 v[20:23], v[196:199], v[188:191], v[20:23]
	s_waitcnt lgkmcnt(2)
	v_mfma_f32_16x16x32_bf16 v[88:91], v[200:203], v[176:179], v[88:91]
	v_mfma_f32_16x16x32_bf16 v[52:55], v[200:203], v[180:183], v[52:55]
	v_mfma_f32_16x16x32_bf16 v[28:31], v[200:203], v[184:187], v[28:31]
	v_mfma_f32_16x16x32_bf16 v[12:15], v[200:203], v[188:191], v[12:15]
	s_waitcnt lgkmcnt(1)
; template <int EPI>
; DI void gemm_tile(const Params& p, const u16* __restrict__ A, int lda, const u16* __restrict__ Bt, int ldb, int K, int m0, int n0,
;                   char* smem, u16* Cb, int ldc) {
;     ...
; #pragma unroll
;     for (int ks = 0; ks < 2; ++ks) {
;       bf16x8 bfr[4];
; #pragma unroll
;       for (int n = 0; n < 4; ++n) bfr[n] = *(const bf16x8*)(cB + n * 16 * LSTR + (ks ? fo1 : fo0));
; #pragma unroll
;       for (int mh = 0; mh < 2; ++mh) {
;         bf16x8 af[4];
; #pragma unroll
;         for (int m = 0; m < 4; ++m) af[m] = *(const bf16x8*)(cA + (mh * 4 + m) * 16 * LSTR + (ks ? fo1 : fo0));
;         __builtin_amdgcn_s_setprio(1);
; #pragma unroll
;         for (int m = 0; m < 4; ++m)
; #pragma unroll
;           for (int n = 0; n < 4; ++n)
;             acc[mh * 4 + m][n] = EpiSwap<EPI>::v ? __builtin_amdgcn_mfma_f32_16x16x32_bf16(bfr[n], af[m], acc[mh * 4 + m][n], 0, 0, 0)
;                                                  : __builtin_amdgcn_mfma_f32_16x16x32_bf16(af[m], bfr[n], acc[mh * 4 + m][n], 0, 0, 0);
;         __builtin_amdgcn_s_setprio(0);
;       }
;     }
;   }
	v_mfma_f32_16x16x32_bf16 v[68:71], v[204:207], v[176:179], v[68:71]
	v_mfma_f32_16x16x32_bf16 v[36:39], v[204:207], v[180:183], v[36:39]
	v_mfma_f32_16x16x32_bf16 v[16:19], v[204:207], v[184:187], v[16:19]
	v_mfma_f32_16x16x32_bf16 v[4:7], v[204:207], v[188:191], v[4:7]
	s_waitcnt lgkmcnt(0)
	v_mfma_f32_16x16x32_bf16 v[48:51], v[208:211], v[176:179], v[48:51]
	v_mfma_f32_16x16x32_bf16 v[24:27], v[208:211], v[180:183], v[24:27]
	v_mfma_f32_16x16x32_bf16 v[8:11], v[208:211], v[184:187], v[8:11]
	v_mfma_f32_16x16x32_bf16 v[0:3], v[208:211], v[188:191], v[0:3]
	s_setprio 0
	v_add_u32_e32 v188, v192, v174
	v_add_u32_e32 v175, v175, v174
	ds_read_b128 v[176:179], v188 offset:32768
	ds_read_b128 v[180:183], v188 offset:34816
	ds_read_b128 v[184:187], v188 offset:36864
	ds_read_b128 v[188:191], v188 offset:38912
	ds_read_b128 v[196:199], v175
	ds_read_b128 v[200:203], v175 offset:2048
	ds_read_b128 v[204:207], v175 offset:4096
	ds_read_b128 v[208:211], v175 offset:6144
	s_setprio 1
	s_waitcnt lgkmcnt(3)
	v_mfma_f32_16x16x32_bf16 v[156:159], v[196:199], v[176:179], v[156:159]
	v_mfma_f32_16x16x32_bf16 v[108:111], v[196:199], v[180:183], v[108:111]
	v_mfma_f32_16x16x32_bf16 v[96:99], v[196:199], v[184:187], v[96:99]
	v_mfma_f32_16x16x32_bf16 v[76:79], v[196:199], v[188:191], v[76:79]
	s_waitcnt lgkmcnt(2)
	v_mfma_f32_16x16x32_bf16 v[140:143], v[200:203], v[176:179], v[140:143]
	v_mfma_f32_16x16x32_bf16 v[104:107], v[200:203], v[180:183], v[104:107]
	v_mfma_f32_16x16x32_bf16 v[84:87], v[200:203], v[184:187], v[84:87]
	v_mfma_f32_16x16x32_bf16 v[60:63], v[200:203], v[188:191], v[60:63]
	s_waitcnt lgkmcnt(1)
	v_mfma_f32_16x16x32_bf16 v[116:119], v[204:207], v[176:179], v[116:119]
	v_mfma_f32_16x16x32_bf16 v[92:95], v[204:207], v[180:183], v[92:95]
	v_mfma_f32_16x16x32_bf16 v[72:75], v[204:207], v[184:187], v[72:75]
	v_mfma_f32_16x16x32_bf16 v[44:47], v[204:207], v[188:191], v[44:47]
	s_waitcnt lgkmcnt(0)
	v_mfma_f32_16x16x32_bf16 v[112:115], v[208:211], v[176:179], v[112:115]
	v_mfma_f32_16x16x32_bf16 v[80:83], v[208:211], v[180:183], v[80:83]
	v_mfma_f32_16x16x32_bf16 v[56:59], v[208:211], v[184:187], v[56:59]
	v_mfma_f32_16x16x32_bf16 v[32:35], v[208:211], v[188:191], v[32:35]
	s_setprio 0
	ds_read_b128 v[196:199], v175 offset:8192
	ds_read_b128 v[200:203], v175 offset:10240
	ds_read_b128 v[204:207], v175 offset:12288
	ds_read_b128 v[208:211], v175 offset:14336
	s_setprio 1
	s_waitcnt lgkmcnt(3)
	v_mfma_f32_16x16x32_bf16 v[100:103], v[196:199], v[176:179], v[100:103]
	v_mfma_f32_16x16x32_bf16 v[64:67], v[196:199], v[180:183], v[64:67]
	v_mfma_f32_16x16x32_bf16 v[40:43], v[196:199], v[184:187], v[40:43]
	v_mfma_f32_16x16x32_bf16 v[20:23], v[196:199], v[188:191], v[20:23]
	s_waitcnt lgkmcnt(2)
	v_mfma_f32_16x16x32_bf16 v[88:91], v[200:203], v[176:179], v[88:91]
	v_mfma_f32_16x16x32_bf16 v[52:55], v[200:203], v[180:183], v[52:55]
	v_mfma_f32_16x16x32_bf16 v[28:31], v[200:203], v[184:187], v[28:31]
	v_mfma_f32_16x16x32_bf16 v[12:15], v[200:203], v[188:191], v[12:15]
	s_waitcnt lgkmcnt(1)
	v_mfma_f32_16x16x32_bf16 v[68:71], v[204:207], v[176:179], v[68:71]
	v_mfma_f32_16x16x32_bf16 v[36:39], v[204:207], v[180:183], v[36:39]
	v_mfma_f32_16x16x32_bf16 v[16:19], v[204:207], v[184:187], v[16:19]
	v_mfma_f32_16x16x32_bf16 v[4:7], v[204:207], v[188:191], v[4:7]
	s_waitcnt lgkmcnt(0)
	v_mfma_f32_16x16x32_bf16 v[48:51], v[208:211], v[176:179], v[48:51]
	v_mfma_f32_16x16x32_bf16 v[24:27], v[208:211], v[180:183], v[24:27]
	v_mfma_f32_16x16x32_bf16 v[8:11], v[208:211], v[184:187], v[8:11]
	v_mfma_f32_16x16x32_bf16 v[0:3], v[208:211], v[188:191], v[0:3]
	s_setprio 0
	s_cmp_lg_u32 s15, 16
	s_mov_b32 s14, s16
	s_cbranch_scc0 .LBB0_2004

; __global__ void __launch_bounds__(NTHREADS) fwd_megakernel(Params p) {
;   extern __shared__ __attribute__((aligned(16))) char smem[];
;   cg::grid_group grid = cg::this_grid();
	.amdhsa_kernel _Z14fwd_megakernel6Params
		.amdhsa_group_segment_fixed_size 0
		.amdhsa_private_segment_fixed_size 0
		.amdhsa_kernarg_size 648
		.amdhsa_user_sgpr_count 2
		.amdhsa_user_sgpr_dispatch_ptr 0
		.amdhsa_user_sgpr_queue_ptr 0
		.amdhsa_user_sgpr_kernarg_segment_ptr 1
		.amdhsa_user_sgpr_dispatch_id 0
		.amdhsa_user_sgpr_kernarg_preload_length 0
		.amdhsa_user_sgpr_kernarg_preload_offset 0
		.amdhsa_user_sgpr_private_segment_size 0
		.amdhsa_uses_dynamic_stack 0
		.amdhsa_enable_private_segment 0
		.amdhsa_system_sgpr_workgroup_id_x 1
		.amdhsa_system_sgpr_workgroup_id_y 0
		.amdhsa_system_sgpr_workgroup_id_z 0
		.amdhsa_system_sgpr_workgroup_info 0
		.amdhsa_system_vgpr_workitem_id 2
		.amdhsa_next_free_vgpr 256
		.amdhsa_next_free_sgpr 102
		.amdhsa_accum_offset 256
		.amdhsa_reserve_vcc 1
		.amdhsa_float_round_mode_32 0
		.amdhsa_float_round_mode_16_64 0
		.amdhsa_float_denorm_mode_32 3
		.amdhsa_float_denorm_mode_16_64 3
		.amdhsa_dx10_clamp 1
		.amdhsa_ieee_mode 1
		.amdhsa_fp16_overflow 0
		.amdhsa_tg_split 0
		.amdhsa_exception_fp_ieee_invalid_op 0
		.amdhsa_exception_fp_denorm_src 0
		.amdhsa_exception_fp_ieee_div_zero 0
		.amdhsa_exception_fp_ieee_overflow 0
		.amdhsa_exception_fp_ieee_underflow 0
		.amdhsa_exception_fp_ieee_inexact 0
		.amdhsa_exception_int_div_zero 0
	.end_amdhsa_kernel

; __global__ void __launch_bounds__(NTHREADS) fwd_megakernel(Params p) {
;   extern __shared__ __attribute__((aligned(16))) char smem[];
;   cg::grid_group grid = cg::this_grid();
amdhsa.kernels:
  - .agpr_count:     0
    .args:
      - .offset:         0
        .size:           392
        .value_kind:     by_value
      - .offset:         392
        .size:           4
        .value_kind:     hidden_block_count_x
      - .offset:         396
        .size:           4
        .value_kind:     hidden_block_count_y
      - .offset:         400
        .size:           4
        .value_kind:     hidden_block_count_z
      - .offset:         404
        .size:           2
        .value_kind:     hidden_group_size_x
      - .offset:         406
        .size:           2
        .value_kind:     hidden_group_size_y
      - .offset:         408
        .size:           2
        .value_kind:     hidden_group_size_z
      - .offset:         410
        .size:           2
        .value_kind:     hidden_remainder_x
      - .offset:         412
        .size:           2
        .value_kind:     hidden_remainder_y
      - .offset:         414
        .size:           2
        .value_kind:     hidden_remainder_z
      - .offset:         432
        .size:           8
        .value_kind:     hidden_global_offset_x
      - .offset:         440
        .size:           8
        .value_kind:     hidden_global_offset_y
      - .offset:         448
        .size:           8
        .value_kind:     hidden_global_offset_z
      - .offset:         456
        .size:           2
        .value_kind:     hidden_grid_dims
      - .offset:         480
        .size:           8
        .value_kind:     hidden_multigrid_sync_arg
      - .offset:         512
        .size:           4
        .value_kind:     hidden_dynamic_lds_size
    .group_segment_fixed_size: 0
    .kernarg_segment_align: 8
    .kernarg_segment_size: 648
    .language:       OpenCL C
    .language_version:
      - 2
      - 0
    .max_flat_workgroup_size: 512
    .name:           _Z14fwd_megakernel6Params
    .private_segment_fixed_size: 0
    .sgpr_count:     108
    .sgpr_spill_count: 62
    .symbol:         _Z14fwd_megakernel6Params.kd
    .uniform_work_group_size: 1
    .uses_dynamic_stack: false
    .vgpr_count:     256
    .vgpr_spill_count: 0
    .wavefront_size: 64
